# attention (prompt items): mask rows of the item staged in LDS once by LDS-DMA, main loop reads mask words with ds_read_b32 instead of 4 scattered global loads per step
# speedup vs baseline: 1.0241x; 1.0213x over previous
; DI float bf2f(bfr b) { return __uint_as_float(((unsigned)b) << 16); }
; DI void attn_block(const Params& p, int isP, int sq, int c, int h) {
;   const int tid = get_tid(), wid = __builtin_amdgcn_readfirstlane(tid >> 6), lane = tid & 63, fr = lane & 15, fq = lane >> 4;
;   int T0, nqt, nadm, rowbase, vld;
;   const bfr *kb, *vt;
;   if (isP) {
;     if (c == 0) { T0 = 0; nqt = 1; nadm = 16; } else { T0 = 16 + 64 * (c - 1); nqt = 4; nadm = 16 + 64 * c; }
;     rowbase = sq * T_P;
;     kb = (const bfr*)(p.ws + W_KBP) + (long)sq * KP_PAD * 512;
;     vt = (const bfr*)(p.ws + W_VTP) + (long)sq * 512 * KP_PAD;
;     vld = KP_PAD;
;   } else {
;     T0 = 0; nqt = 4; nadm = S_S; rowbase = ROWS_P + sq * 64;
;     kb = (const bfr*)(p.ws + W_KBS) + (long)sq * S_S * 512;
;     vt = (const bfr*)(p.ws + W_VTS) + (long)sq * 512 * S_S;
;     vld = S_S;
;   }
;   const int nsteps = (nadm + 31) >> 5;
;   const int qrow0 = rowbase + T0;
;   const bfr* qb = (const bfr*)(p.ws + W_QB);
;   const unsigned* maskg = (const unsigned*)(p.ws + W_MASK);
;   bf16x8 qf[4][2];
; #pragma unroll
;   for (int qt = 0; qt < 4; ++qt)
; #pragma unroll
;     for (int ks = 0; ks < 2; ++ks) {
;       int r = qrow0 + (qt < nqt ? qt * 16 : 0) + fr;
;       qf[qt][ks] = *(const bf16x8*)(qb + (long)r * 512 + h * 64 + ks * 32 + fq * 8);
;     }
;   f32x4 o[4][4];
; #pragma unroll
;   for (int qt = 0; qt < 4; ++qt)
; #pragma unroll
;     for (int dt = 0; dt < 4; ++dt) o[qt][dt] = f32x4{0.f, 0.f, 0.f, 0.f};
;   const float sc2 = 0.125f * 1.4426950408889634f;
;   const float kmax2 = ((const float*)(p.ws + W_KMAX))[(isP ? sq : NB_P + sq) * 8 + h];
;   float mref[4], lsum[4] = {0.f, 0.f, 0.f, 0.f};
;   const unsigned* mrow[4];
; #pragma unroll
;   for (int qt = 0; qt < 4; ++qt) {
;     float ss = 0.f;
; #pragma unroll
;     for (int ks = 0; ks < 2; ++ks)
; #pragma unroll
;       for (int i = 0; i < 8; ++i) { float a = bf2f((bfr)qf[qt][ks][i]); ss += a * a; }
;     ss += __shfl_xor(ss, 16);
;     ss += __shfl_xor(ss, 32);
;     mref[qt] = sqrtf(ss * kmax2) * sc2;
;     mrow[qt] = maskg + (long)(qrow0 + (qt < nqt ? qt * 16 : 0) + fr) * MW;
;   }
.LBB0_4859:
	s_ashr_i32 s0, s18, 5
	s_sub_i32 s0, 64, s0
	s_bfe_u32 s22, s18, 0x20003
	s_lshl_b32 s1, s0, 6
	s_mul_i32 s7, s22, 0x1010
	v_mov_b32_e32 v141, v158
	s_add_i32 s1, s1, s7
	s_lshl_b32 s0, s0, 1
	s_and_b32 s21, s0, 0x7fffffe
	v_and_b32_e32 v100, 15, v141
	s_sub_i32 s0, s1, 48
	v_or_b32_e32 v138, s0, v100
	s_lshl_b32 s0, s18, 6
	v_readfirstlane_b32 s19, v141
	s_and_b32 s7, s0, 0x1c0
	s_ashr_i32 s6, s19, 6
	s_lshl_b32 s20, s7, 1
	s_add_u32 s0, s12, s20
	s_addc_u32 s1, s13, 0
	v_and_b32_e32 v128, 48, v141
	v_ashrrev_i32_e32 v139, 31, v138
	v_lshl_add_u64 v[0:1], s[0:1], 0, v[128:129]
	v_lshlrev_b64 v[2:3], 10, v[138:139]
	v_lshl_add_u64 v[2:3], v[0:1], 0, v[2:3]
	global_load_dwordx4 v[16:19], v[2:3], off
	global_load_dwordx4 v[24:27], v[2:3], off offset:64
	v_add_u32_e32 v96, 16, v138
	v_ashrrev_i32_e32 v97, 31, v96
	v_lshlrev_b64 v[2:3], 10, v[96:97]
	v_lshl_add_u64 v[2:3], v[0:1], 0, v[2:3]
	global_load_dwordx4 v[36:39], v[2:3], off
	global_load_dwordx4 v[44:47], v[2:3], off offset:64
	v_and_b32_e32 v3, 64, v164
	v_xor_b32_e32 v2, 16, v164
	v_add_u32_e32 v5, 64, v3
	v_add_u32_e32 v136, 32, v138
	s_waitcnt vmcnt(4)
	v_xor_b32_e32 v4, 32, v164
	v_cmp_lt_i32_e32 vcc, v2, v5
	v_ashrrev_i32_e32 v137, 31, v136
	v_add_u32_e32 v98, 48, v138
	v_cndmask_b32_e32 v7, v164, v2, vcc
	v_lshlrev_b64 v[2:3], 10, v[136:137]
	v_cmp_lt_i32_e32 vcc, v4, v5
	v_lshl_add_u64 v[2:3], v[0:1], 0, v[2:3]
	v_ashrrev_i32_e32 v99, 31, v98
	v_cndmask_b32_e32 v4, v164, v4, vcc
	global_load_dwordx4 v[48:51], v[2:3], off
	v_lshlrev_b32_e32 v139, 2, v4
	v_lshlrev_b64 v[4:5], 10, v[98:99]
	v_lshl_add_u64 v[0:1], v[0:1], 0, v[4:5]
	global_load_dwordx4 v[52:55], v[2:3], off offset:64
	global_load_dwordx4 v[56:59], v[0:1], off
	global_load_dwordx4 v[60:63], v[0:1], off offset:64
	v_bfe_u32 v6, v141, 4, 2
	v_lshlrev_b32_e32 v140, 3, v6
	v_lshlrev_b32_e32 v180, 2, v7
	v_mov_b32_e32 v143, 0
	v_readfirstlane_b32 s100, v138
	v_readlane_b32 s98, v251, 22
	v_readlane_b32 s99, v251, 23
	s_mul_i32 s101, s100, 0x210
	s_add_u32 s98, s98, s101
	s_addc_u32 s99, s99, 0
	v_and_b32_e32 v206, 63, v141
	v_lshlrev_b32_e32 v206, 4, v206
	v_mov_b32_e32 v207, 0
	v_lshl_add_u64 v[206:207], s[98:99], 0, v[206:207]
	s_lshl_b32 s100, s6, 10
	v_mov_b32_e32 v209, 0
.Lmf_loop:
	v_mov_b32_e32 v208, s100
	s_add_i32 s101, s100, 0x80
	s_mov_b32 m0, s101
	v_lshl_add_u64 v[210:211], v[206:207], 0, v[208:209]
	global_load_lds_dwordx4 v[210:211], off
	s_addk_i32 s100, 0x1000
	s_cmpk_lt_u32 s100, 0x8400
	s_cbranch_scc1 .Lmf_loop
	s_cmp_gt_i32 s6, s21
	v_mov_b32_e32 v142, v143
	v_mov_b32_e32 v147, v143
	v_mov_b32_e32 v146, v143
	v_mov_b32_e32 v35, v143
	v_mov_b32_e32 v43, v143
	v_mov_b32_e32 v42, v143
	v_mov_b32_e32 v41, v143
	v_mov_b32_e32 v40, v143
	v_mov_b32_e32 v71, v143
	v_mov_b32_e32 v70, v143
	v_mov_b32_e32 v69, v143
	v_mov_b32_e32 v68, v143
	v_mov_b32_e32 v75, v143
	v_mov_b32_e32 v74, v143
	v_mov_b32_e32 v73, v143
	v_mov_b32_e32 v72, v143
	v_mov_b32_e32 v79, v143
	v_mov_b32_e32 v78, v143
	v_mov_b32_e32 v77, v143
	v_mov_b32_e32 v76, v143
	v_mov_b32_e32 v83, v143
	v_mov_b32_e32 v82, v143
	v_mov_b32_e32 v81, v143
	v_mov_b32_e32 v80, v143
	v_mov_b32_e32 v87, v143
	v_mov_b32_e32 v86, v143
	v_mov_b32_e32 v85, v143
	v_mov_b32_e32 v84, v143
	v_mov_b32_e32 v91, v143
	v_mov_b32_e32 v90, v143
	v_mov_b32_e32 v89, v143
	v_mov_b32_e32 v88, v143
	v_mov_b32_e32 v95, v143
	v_mov_b32_e32 v94, v143
	v_mov_b32_e32 v93, v143
	v_mov_b32_e32 v92, v143
	v_mov_b32_e32 v67, v143
	v_mov_b32_e32 v66, v143
	v_mov_b32_e32 v65, v143
	v_mov_b32_e32 v64, v143
	s_waitcnt vmcnt(7)
	v_and_b32_e32 v1, 0xffff0000, v16
	v_lshlrev_b32_e32 v0, 16, v16
	v_mul_f32_e32 v1, v1, v1
	v_lshlrev_b32_e32 v2, 16, v17
	v_fmac_f32_e32 v1, v0, v0
	v_and_b32_e32 v3, 0xffff0000, v17
	v_fmac_f32_e32 v1, v2, v2
	v_lshlrev_b32_e32 v4, 16, v18
	v_fmac_f32_e32 v1, v3, v3
	v_and_b32_e32 v5, 0xffff0000, v18
	v_fmac_f32_e32 v1, v4, v4
	v_lshlrev_b32_e32 v6, 16, v19
	v_fmac_f32_e32 v1, v5, v5
	v_and_b32_e32 v7, 0xffff0000, v19
	v_fmac_f32_e32 v1, v6, v6
	s_waitcnt vmcnt(6)
	v_lshlrev_b32_e32 v8, 16, v24
	v_fmac_f32_e32 v1, v7, v7
	v_and_b32_e32 v9, 0xffff0000, v24
	v_fmac_f32_e32 v1, v8, v8
	v_lshlrev_b32_e32 v10, 16, v25
	v_fmac_f32_e32 v1, v9, v9
	v_and_b32_e32 v11, 0xffff0000, v25
	v_fmac_f32_e32 v1, v10, v10
	v_lshlrev_b32_e32 v12, 16, v26
	v_fmac_f32_e32 v1, v11, v11
	v_and_b32_e32 v13, 0xffff0000, v26
	v_fmac_f32_e32 v1, v12, v12
	v_lshlrev_b32_e32 v14, 16, v27
	v_fmac_f32_e32 v1, v13, v13
	v_and_b32_e32 v15, 0xffff0000, v27
	v_fmac_f32_e32 v1, v14, v14
	v_fmac_f32_e32 v1, v15, v15
	ds_bpermute_b32 v2, v180, v1
	s_waitcnt vmcnt(5)
	v_and_b32_e32 v21, 0xffff0000, v36
	s_waitcnt vmcnt(3)
	v_and_b32_e32 v3, 0xffff0000, v48
	s_waitcnt vmcnt(1)
	v_and_b32_e32 v5, 0xffff0000, v56
	v_lshlrev_b32_e32 v20, 16, v36
	v_mul_f32_e32 v0, v21, v21
	s_waitcnt lgkmcnt(0)
	v_add_f32_e32 v103, v1, v2
	v_lshlrev_b32_e32 v2, 16, v48
	v_mul_f32_e32 v3, v3, v3
	v_lshlrev_b32_e32 v4, 16, v56
	v_mul_f32_e32 v5, v5, v5
	v_lshlrev_b32_e32 v22, 16, v37
	v_fmac_f32_e32 v0, v20, v20
	v_fmac_f32_e32 v3, v2, v2
	v_lshlrev_b32_e32 v2, 16, v49
	v_fmac_f32_e32 v5, v4, v4
	v_lshlrev_b32_e32 v4, 16, v57
	v_and_b32_e32 v23, 0xffff0000, v37
	v_fmac_f32_e32 v0, v22, v22
	v_fmac_f32_e32 v3, v2, v2
	v_and_b32_e32 v2, 0xffff0000, v49
	v_fmac_f32_e32 v5, v4, v4
	v_and_b32_e32 v4, 0xffff0000, v57
	v_lshlrev_b32_e32 v28, 16, v38
	v_fmac_f32_e32 v0, v23, v23
	v_fmac_f32_e32 v3, v2, v2
	v_lshlrev_b32_e32 v2, 16, v50
	v_fmac_f32_e32 v5, v4, v4
	v_lshlrev_b32_e32 v4, 16, v58
	v_and_b32_e32 v29, 0xffff0000, v38
	v_fmac_f32_e32 v0, v28, v28
	v_fmac_f32_e32 v3, v2, v2
	v_and_b32_e32 v2, 0xffff0000, v50
	v_fmac_f32_e32 v5, v4, v4
	v_and_b32_e32 v4, 0xffff0000, v58
	v_lshlrev_b32_e32 v30, 16, v39
	v_fmac_f32_e32 v0, v29, v29
	v_fmac_f32_e32 v3, v2, v2
	v_lshlrev_b32_e32 v2, 16, v51
	v_fmac_f32_e32 v5, v4, v4
	v_lshlrev_b32_e32 v4, 16, v59
	v_and_b32_e32 v31, 0xffff0000, v39
	v_fmac_f32_e32 v0, v30, v30
	v_fmac_f32_e32 v3, v2, v2
	v_and_b32_e32 v2, 0xffff0000, v51
	v_fmac_f32_e32 v5, v4, v4
	v_and_b32_e32 v4, 0xffff0000, v59
	v_lshlrev_b32_e32 v32, 16, v44
	v_fmac_f32_e32 v0, v31, v31
	v_fmac_f32_e32 v3, v2, v2
	v_lshlrev_b32_e32 v2, 16, v52
	v_fmac_f32_e32 v5, v4, v4
	s_waitcnt vmcnt(0)
	s_barrier
; DI float bf2f(bfr b) { return __uint_as_float(((unsigned)b) << 16); }
; DI void attn_block(const Params& p, int isP, int sq, int c, int h) {
;     ...
;   for (int qt = 0; qt < 4; ++qt) {
;     float ss = 0.f;
; #pragma unroll
;     for (int ks = 0; ks < 2; ++ks)
; #pragma unroll
;       for (int i = 0; i < 8; ++i) { float a = bf2f((bfr)qf[qt][ks][i]); ss += a * a; }
;     ss += __shfl_xor(ss, 16);
;     ss += __shfl_xor(ss, 32);
;     mref[qt] = sqrtf(ss * kmax2) * sc2;
;     mrow[qt] = maskg + (long)(qrow0 + (qt < nqt ? qt * 16 : 0) + fr) * MW;
;   }
;   const int kofs = (fr >> 2) * 8 + (fr & 3);
;   const bfr* kptr = kb + (long)kofs * 512 + h * 64 + fq * 8;
;   const bfr* vptr = vt + (long)(h * 64 + fr) * vld + fq * 8;
;   if (wid < nsteps) {
;     int s = wid;
;     const bfr* pa0 = kptr + (long)s * 32 * 512;
;     bf16x8 ka0 = *(const bf16x8*)pa0, ka1 = *(const bf16x8*)(pa0 + 32);
;     bf16x8 kb0 = *(const bf16x8*)(pa0 + 4 * 512), kb1 = *(const bf16x8*)(pa0 + 4 * 512 + 32);
;     bf16x8 vf[4];
; #pragma unroll
;     for (int dt = 0; dt < 4; ++dt) vf[dt] = *(const bf16x8*)(vptr + (long)dt * 16 * vld + s * 32);
;     unsigned mw[4];
; #pragma unroll
;     for (int qt = 0; qt < 4; ++qt) mw[qt] = mrow[qt][s];
	v_lshlrev_b32_e32 v4, 16, v60
	v_and_b32_e32 v33, 0xffff0000, v44
	v_fmac_f32_e32 v0, v32, v32
	v_fmac_f32_e32 v3, v2, v2
	v_and_b32_e32 v2, 0xffff0000, v52
	v_fmac_f32_e32 v5, v4, v4
	v_and_b32_e32 v4, 0xffff0000, v60
	v_lshlrev_b32_e32 v34, 16, v45
	v_fmac_f32_e32 v0, v33, v33
	v_fmac_f32_e32 v3, v2, v2
	v_lshlrev_b32_e32 v2, 16, v53
	v_fmac_f32_e32 v5, v4, v4
	v_lshlrev_b32_e32 v4, 16, v61
	v_fmac_f32_e32 v0, v34, v34
	v_and_b32_e32 v1, 0xffff0000, v45
	v_fmac_f32_e32 v3, v2, v2
	v_and_b32_e32 v2, 0xffff0000, v53
	v_fmac_f32_e32 v5, v4, v4
	v_and_b32_e32 v4, 0xffff0000, v61
	v_fmac_f32_e32 v0, v1, v1
	v_lshlrev_b32_e32 v1, 16, v46
	v_fmac_f32_e32 v3, v2, v2
	v_lshlrev_b32_e32 v2, 16, v54
	v_fmac_f32_e32 v5, v4, v4
	v_lshlrev_b32_e32 v4, 16, v62
	v_fmac_f32_e32 v0, v1, v1
	v_and_b32_e32 v1, 0xffff0000, v46
	v_fmac_f32_e32 v3, v2, v2
	v_and_b32_e32 v2, 0xffff0000, v54
	v_fmac_f32_e32 v5, v4, v4
	v_and_b32_e32 v4, 0xffff0000, v62
	v_fmac_f32_e32 v0, v1, v1
	v_lshlrev_b32_e32 v1, 16, v47
	v_fmac_f32_e32 v3, v2, v2
	v_lshlrev_b32_e32 v2, 16, v55
	v_fmac_f32_e32 v5, v4, v4
	v_lshlrev_b32_e32 v4, 16, v63
	v_fmac_f32_e32 v0, v1, v1
	v_and_b32_e32 v1, 0xffff0000, v47
	v_fmac_f32_e32 v3, v2, v2
	v_and_b32_e32 v2, 0xffff0000, v55
	v_fmac_f32_e32 v5, v4, v4
	v_and_b32_e32 v4, 0xffff0000, v63
	v_fmac_f32_e32 v0, v1, v1
	v_fmac_f32_e32 v3, v2, v2
	v_fmac_f32_e32 v5, v4, v4
	ds_bpermute_b32 v1, v180, v0
	ds_bpermute_b32 v2, v180, v3
	ds_bpermute_b32 v4, v180, v5
	ds_bpermute_b32 v104, v139, v103
	v_mov_b32_e32 v7, v143
	s_waitcnt lgkmcnt(3)
	v_add_f32_e32 v105, v0, v1
	s_waitcnt lgkmcnt(2)
	v_add_f32_e32 v101, v3, v2
	s_waitcnt lgkmcnt(1)
	v_add_f32_e32 v97, v5, v4
	ds_bpermute_b32 v106, v139, v105
	ds_bpermute_b32 v102, v139, v101
	ds_bpermute_b32 v99, v139, v97
	v_mov_b32_e32 v3, v143
	v_mov_b32_e32 v2, v143
	v_mov_b32_e32 v1, v143
	v_mov_b32_e32 v0, v143
	v_mov_b32_e32 v6, v143
	v_mov_b32_e32 v5, v143
	v_mov_b32_e32 v4, v143
	v_mov_b32_e32 v11, v143
	v_mov_b32_e32 v10, v143
	v_mov_b32_e32 v9, v143
	v_mov_b32_e32 v8, v143
	v_mov_b32_e32 v15, v143
	v_mov_b32_e32 v14, v143
	v_mov_b32_e32 v13, v143
	v_mov_b32_e32 v12, v143
	v_mov_b32_e32 v23, v143
	v_mov_b32_e32 v22, v143
	v_mov_b32_e32 v21, v143
	v_mov_b32_e32 v20, v143
	v_mov_b32_e32 v31, v143
	v_mov_b32_e32 v30, v143
	v_mov_b32_e32 v29, v143
	v_mov_b32_e32 v28, v143
	v_mov_b32_e32 v34, v143
	v_mov_b32_e32 v33, v143
	v_mov_b32_e32 v32, v143
	s_cbranch_scc1 .LBB0_4862
	s_mul_i32 s22, s22, 0x408000
	s_add_u32 s8, s10, s22
	s_addc_u32 s9, s11, 0
	s_and_b32 s0, s18, 31
	s_lshl_b32 s0, s0, 2
	v_mov_b32_e32 v0, s0
	global_load_dword v0, v0, s[2:3]
	s_waitcnt lgkmcnt(3)
	v_add_f32_e32 v1, v103, v104
	s_mov_b32 s23, 0xf800000
	v_readlane_b32 s24, v249, 0
	v_mov_b32_e32 v64, 0
	v_readlane_b32 s25, v249, 1
	v_mov_b32_e32 v137, v140
	v_mov_b32_e32 v65, v64
	v_mov_b32_e32 v66, v64
	v_mov_b32_e32 v67, v64
	v_mov_b32_e32 v92, v64
	v_mov_b32_e32 v93, v64
	v_mov_b32_e32 v94, v64
	v_mov_b32_e32 v95, v64
	v_mov_b32_e32 v88, v64
	v_mov_b32_e32 v89, v64
	v_mov_b32_e32 v90, v64
	v_mov_b32_e32 v91, v64
	v_mov_b32_e32 v84, v64
	v_mov_b32_e32 v85, v64
	v_mov_b32_e32 v86, v64
	v_mov_b32_e32 v87, v64
	v_mov_b32_e32 v80, v64
	v_mov_b32_e32 v81, v64
	v_mov_b32_e32 v82, v64
	v_mov_b32_e32 v83, v64
	v_mov_b32_e32 v76, v64
	v_mov_b32_e32 v77, v64
	v_mov_b32_e32 v78, v64
	v_mov_b32_e32 v79, v64
	v_mov_b32_e32 v72, v64
	v_mov_b32_e32 v73, v64
	v_mov_b32_e32 v74, v64
	v_mov_b32_e32 v75, v64
	v_mov_b32_e32 v68, v64
	v_mov_b32_e32 v69, v64
	v_mov_b32_e32 v70, v64
	v_mov_b32_e32 v71, v64
	v_mov_b32_e32 v40, v64
	v_mov_b32_e32 v41, v64
	v_mov_b32_e32 v42, v64
	v_mov_b32_e32 v43, v64
	v_mov_b32_e32 v32, v64
	v_mov_b32_e32 v33, v64
	v_mov_b32_e32 v34, v64
	v_mov_b32_e32 v35, v64
	v_mov_b32_e32 v28, v64
	v_mov_b32_e32 v29, v64
	v_mov_b32_e32 v30, v64
	v_mov_b32_e32 v31, v64
	v_mov_b32_e32 v20, v64
	v_mov_b32_e32 v21, v64
	v_mov_b32_e32 v22, v64
	v_mov_b32_e32 v23, v64
	v_mov_b32_e32 v12, v64
	v_mov_b32_e32 v13, v64
	v_mov_b32_e32 v14, v64
	v_mov_b32_e32 v15, v64
	v_mov_b32_e32 v8, v64
	v_mov_b32_e32 v9, v64
	v_mov_b32_e32 v10, v64
	v_mov_b32_e32 v11, v64
	v_mov_b32_e32 v5, v64
	v_mov_b32_e32 v6, v64
	v_mov_b32_e32 v7, v64
	v_mov_b32_e32 v146, v64
	v_mov_b32_e32 v147, v64
	v_mov_b32_e32 v142, v64
	v_mov_b32_e32 v143, v64
	v_readlane_b32 s26, v249, 2
	v_readlane_b32 s27, v249, 3
	s_waitcnt vmcnt(0)
	v_mul_f32_e32 v1, v0, v1
	v_cmp_gt_f32_e32 vcc, s23, v1
	v_mul_f32_e32 v2, 0x4f800000, v1
	s_nop 0
	v_cndmask_b32_e32 v1, v1, v2, vcc
	v_sqrt_f32_e32 v2, v1
	s_nop 0
	v_add_u32_e32 v3, -1, v2
	v_fma_f32 v4, -v3, v2, v1
	v_cmp_ge_f32_e64 s[0:1], 0, v4
	v_add_u32_e32 v4, 1, v2
	s_nop 0
	v_cndmask_b32_e64 v3, v2, v3, s[0:1]
	v_fma_f32 v2, -v4, v2, v1
	v_cmp_lt_f32_e64 s[0:1], 0, v2
	s_nop 1
	v_cndmask_b32_e64 v2, v3, v4, s[0:1]
	v_mul_f32_e32 v3, 0x37800000, v2
	v_cndmask_b32_e32 v2, v2, v3, vcc
	v_cmp_class_f32_e32 vcc, v1, v161
	s_nop 1
	v_cndmask_b32_e32 v1, v2, v1, vcc
	v_mul_f32_e32 v181, 0x3e38aa3b, v1
	s_waitcnt lgkmcnt(2)
	v_add_f32_e32 v1, v105, v106
	v_mul_f32_e32 v1, v0, v1
	v_cmp_gt_f32_e32 vcc, s23, v1
	v_mul_f32_e32 v2, 0x4f800000, v1
	s_nop 0
	v_cndmask_b32_e32 v1, v1, v2, vcc
	v_sqrt_f32_e32 v2, v1
	s_nop 0
	v_add_u32_e32 v3, -1, v2
	v_fma_f32 v4, -v3, v2, v1
	v_cmp_ge_f32_e64 s[0:1], 0, v4
	v_add_u32_e32 v4, 1, v2
	s_nop 0
	v_cndmask_b32_e64 v3, v2, v3, s[0:1]
	v_fma_f32 v2, -v4, v2, v1
	v_cmp_lt_f32_e64 s[0:1], 0, v2
	s_nop 1
	v_cndmask_b32_e64 v2, v3, v4, s[0:1]
	v_mul_f32_e32 v3, 0x37800000, v2
	v_cndmask_b32_e32 v2, v2, v3, vcc
	v_cmp_class_f32_e32 vcc, v1, v161
	s_nop 1
	v_cndmask_b32_e32 v1, v2, v1, vcc
	v_mul_f32_e32 v182, 0x3e38aa3b, v1
	s_waitcnt lgkmcnt(1)
; DI void attn_block(const Params& p, int isP, int sq, int c, int h) {
;     ...
;     mref[qt] = sqrtf(ss * kmax2) * sc2;
;     mrow[qt] = maskg + (long)(qrow0 + (qt < nqt ? qt * 16 : 0) + fr) * MW;
;   }
;   const int kofs = (fr >> 2) * 8 + (fr & 3);
;   const bfr* kptr = kb + (long)kofs * 512 + h * 64 + fq * 8;
;   const bfr* vptr = vt + (long)(h * 64 + fr) * vld + fq * 8;
;   if (wid < nsteps) {
;     int s = wid;
;     const bfr* pa0 = kptr + (long)s * 32 * 512;
;     bf16x8 ka0 = *(const bf16x8*)pa0, ka1 = *(const bf16x8*)(pa0 + 32);
;     bf16x8 kb0 = *(const bf16x8*)(pa0 + 4 * 512), kb1 = *(const bf16x8*)(pa0 + 4 * 512 + 32);
;     bf16x8 vf[4];
; #pragma unroll
;     for (int dt = 0; dt < 4; ++dt) vf[dt] = *(const bf16x8*)(vptr + (long)dt * 16 * vld + s * 32);
;     unsigned mw[4];
; #pragma unroll
;     for (int qt = 0; qt < 4; ++qt) mw[qt] = mrow[qt][s];
;     for (; s < nsteps; s += 4) {
;       const int sn = (s + 4 < nsteps) ? s + 4 : s;
;       const bfr* pa = kptr + (long)sn * 32 * 512;
;       const bf16x8 nka0 = *(const bf16x8*)pa, nka1 = *(const bf16x8*)(pa + 32);
;       const bf16x8 nkb0 = *(const bf16x8*)(pa + 4 * 512), nkb1 = *(const bf16x8*)(pa + 4 * 512 + 32);
;       bf16x8 nvf[4];
; #pragma unroll
;       for (int dt = 0; dt < 4; ++dt) nvf[dt] = *(const bf16x8*)(vptr + (long)dt * 16 * vld + sn * 32);
;       unsigned nmw[4];
; #pragma unroll
;       for (int qt = 0; qt < 4; ++qt) nmw[qt] = mrow[qt][sn];
	v_add_f32_e32 v1, v101, v102
	v_mul_f32_e32 v1, v0, v1
	v_cmp_gt_f32_e32 vcc, s23, v1
	v_mul_f32_e32 v2, 0x4f800000, v1
	s_nop 0
	v_cndmask_b32_e32 v1, v1, v2, vcc
	v_sqrt_f32_e32 v2, v1
	s_nop 0
	v_add_u32_e32 v3, -1, v2
	v_fma_f32 v4, -v3, v2, v1
	v_cmp_ge_f32_e64 s[0:1], 0, v4
	v_add_u32_e32 v4, 1, v2
	s_nop 0
	v_cndmask_b32_e64 v3, v2, v3, s[0:1]
	v_fma_f32 v2, -v4, v2, v1
	v_cmp_lt_f32_e64 s[0:1], 0, v2
	s_nop 1
	v_cndmask_b32_e64 v2, v3, v4, s[0:1]
	v_mul_f32_e32 v3, 0x37800000, v2
	v_cndmask_b32_e32 v2, v2, v3, vcc
	v_cmp_class_f32_e32 vcc, v1, v161
	v_and_b32_e32 v4, 3, v141
	s_nop 0
	v_cndmask_b32_e32 v1, v2, v1, vcc
	v_mul_f32_e32 v183, 0x3e38aa3b, v1
	s_waitcnt lgkmcnt(0)
	v_add_f32_e32 v1, v97, v99
	v_mul_f32_e32 v0, v0, v1
	v_cmp_gt_f32_e32 vcc, s23, v0
	v_mul_f32_e32 v1, 0x4f800000, v0
	s_nop 0
	v_cndmask_b32_e32 v0, v0, v1, vcc
	v_sqrt_f32_e32 v1, v0
	s_nop 0
	v_add_u32_e32 v2, -1, v1
	v_fma_f32 v3, -v2, v1, v0
	v_cmp_ge_f32_e64 s[0:1], 0, v3
	v_add_u32_e32 v3, 1, v1
	s_nop 0
	v_cndmask_b32_e64 v2, v1, v2, s[0:1]
	v_fma_f32 v1, -v3, v1, v0
	v_cmp_lt_f32_e64 s[0:1], 0, v1
	s_nop 1
	v_cndmask_b32_e64 v1, v2, v3, s[0:1]
	v_mul_f32_e32 v2, 0x37800000, v1
	v_cndmask_b32_e32 v1, v1, v2, vcc
	v_cmp_class_f32_e32 vcc, v0, v161
	s_lshl_b32 s0, s6, 5
	v_readlane_b32 s1, v251, 22
	v_cndmask_b32_e32 v0, v1, v0, vcc
	v_mul_f32_e32 v184, 0x3e38aa3b, v0
	v_or_b32_e32 v0, s7, v100
	v_mul_u32_u24_e32 v0, 0x1020, v0
	v_lshlrev_b32_e32 v0, 1, v0
	v_mov_b32_e32 v1, v129
	s_ashr_i32 s7, s6, 31
	v_lshl_add_u64 v[0:1], s[8:9], 0, v[0:1]
	s_lshl_b64 s[8:9], s[6:7], 2
	s_add_u32 s8, s1, s8
	v_readlane_b32 s1, v251, 23
	v_lshlrev_b32_e32 v2, 1, v140
	v_mov_b32_e32 v3, v129
	s_addc_u32 s9, s1, s9
	v_lshl_add_u64 v[144:145], v[0:1], 0, v[2:3]
	v_mov_b64_e32 v[0:1], s[8:9]
	v_mad_i64_i32 v[148:149], s[8:9], v138, s86, v[0:1]
	v_mad_i64_i32 v[150:151], s[8:9], v96, s86, v[0:1]
	v_mad_i64_i32 v[152:153], s[8:9], v136, s86, v[0:1]
	v_mad_i64_i32 v[154:155], s[8:9], v98, s86, v[0:1]
	s_lshl_b64 s[8:9], s[6:7], 15
	s_add_u32 s1, s22, s8
	s_addc_u32 s7, 0, s9
	s_and_b32 s8, s18, 7
	s_lshl_b32 s8, s8, 7
	v_lshlrev_b32_e32 v0, 11, v100
	v_lshlrev_b32_e32 v1, 10, v4
	s_or_b32 s1, s1, s8
	v_and_or_b32 v0, v0, s28, v1
	v_or3_b32 v0, s1, v128, v0
	v_mov_b32_e32 v1, s7
	v_lshl_add_u64 v[156:157], s[24:25], 0, v[0:1]
	s_mov_b32 s7, s6
	v_mov_b32_e32 v4, v64
	v_mov_b32_e32 v0, v64
	v_mov_b32_e32 v1, v64
	v_mov_b32_e32 v2, v64
	v_mov_b32_e32 v3, v64
	s_mov_b32 s8, 0x1655d000
	s_mov_b32 s9, 0x1655c000
	s_mov_b64 s[22:23], 0x20000
	v_mul_u32_u24_e32 v208, 0x210, v100
	v_lshl_add_u32 v208, s6, 2, v208
	v_add_u32_e32 v208, 0x80, v208
.LBB0_4861:
	v_lshl_add_u64 v[96:97], v[156:157], 0, s[36:37]
	v_add_co_u32_e32 v98, vcc, s8, v96
	s_ashr_i32 s1, s0, 31
	s_nop 0
	v_addc_co_u32_e32 v99, vcc, 0, v97, vcc
	v_add_co_u32_e32 v96, vcc, s9, v96
	global_load_dwordx4 v[112:115], v[98:99], off offset:3136
	global_load_dwordx4 v[116:119], v[98:99], off offset:3072
	v_addc_co_u32_e32 v97, vcc, 0, v97, vcc
	global_load_dwordx4 v[120:123], v[96:97], off offset:3136
	global_load_dwordx4 v[124:127], v[96:97], off offset:3072
	ds_read_b32 v128, v208
	ds_read_b32 v159, v208 offset:8448
	v_lshl_add_u64 v[108:109], s[0:1], 1, v[144:145]
	s_mov_b32 s1, 0x20000
	v_add_co_u32_e32 v100, vcc, s1, v108
	s_mov_b32 s1, 0x40000
	s_nop 0
	v_addc_co_u32_e32 v101, vcc, 0, v109, vcc
	v_add_co_u32_e32 v104, vcc, s1, v108
	ds_read_b32 v185, v208 offset:16896
	v_addc_co_u32_e32 v105, vcc, 0, v109, vcc
	s_mov_b32 s1, 0x60000
	ds_read_b32 v204, v208 offset:25344
	s_add_i32 s7, s7, 4
	global_load_dwordx4 v[96:99], v[108:109], off
	v_add_co_u32_e32 v108, vcc, s1, v108
	global_load_dwordx4 v[100:103], v[100:101], off offset:1024
	s_nop 0
	v_addc_co_u32_e32 v109, vcc, 0, v109, vcc
	global_load_dwordx4 v[104:107], v[104:105], off offset:2048
	s_addk_i32 s0, 0x80
	global_load_dwordx4 v[108:111], v[108:109], off offset:3072
	v_add_u32_e32 v208, 16, v208
	v_lshl_add_u64 v[156:157], v[156:157], 0, s[22:23]
	s_cmp_le_i32 s7, s21
	s_waitcnt vmcnt(6)
	v_mfma_f32_16x16x32_bf16 v[186:189], v[116:119], v[16:19], 0
	s_waitcnt vmcnt(4) lgkmcnt(3)
	v_lshrrev_b32_e32 v128, v140, v128
	v_mfma_f32_16x16x32_bf16 v[132:135], v[124:127], v[16:19], 0
	s_waitcnt lgkmcnt(2)
	v_lshrrev_b32_e32 v159, v137, v159
	s_waitcnt lgkmcnt(1)
; #define MFMA16(a, b, c) __builtin_amdgcn_mfma_f32_16x16x32_bf16((a), (b), (c), 0, 0, 0)
; DI void attn_block(const Params& p, int isP, int sq, int c, int h) {
;     ...
;       for (int qt = 0; qt < 4; ++qt) {
;         if (qt < nqt) {
;           f32x4 sa = {0.f, 0.f, 0.f, 0.f}, sb = {0.f, 0.f, 0.f, 0.f};
;           sa = MFMA16(ka0, qf[qt][0], sa); sa = MFMA16(ka1, qf[qt][1], sa);
;           sb = MFMA16(kb0, qf[qt][0], sb); sb = MFMA16(kb1, qf[qt][1], sb);
;           const unsigned mb = (mw[qt] >> (fq * 8)) & 0xFFu;
;           float pr[8];
; #pragma unroll
;           for (int i = 0; i < 4; ++i) {
;             float pa_ = __builtin_amdgcn_exp2f(sa[i] * sc2 - mref[qt]);
;             float pb_ = __builtin_amdgcn_exp2f(sb[i] * sc2 - mref[qt]);
;             pr[i] = ((mb >> i) & 1u) ? pa_ : 0.f;
;             pr[4 + i] = ((mb >> (4 + i)) & 1u) ? pb_ : 0.f;
;           }
;           lsum[qt] += ((pr[0] + pr[1]) + (pr[2] + pr[3])) + ((pr[4] + pr[5]) + (pr[6] + pr[7]));
;           union { unsigned u[4]; bf16x8 v; } pk;
;           pk.u[0] = pack2(pr[0], pr[1]); pk.u[1] = pack2(pr[2], pr[3]); pk.u[2] = pack2(pr[4], pr[5]); pk.u[3] = pack2(pr[6], pr[7]);
; #pragma unroll
;           for (int dt = 0; dt < 4; ++dt) o[qt][dt] = MFMA16(vf[dt], pk.v, o[qt][dt]);
	v_lshrrev_b32_e32 v185, v140, v185
	v_mfma_f32_16x16x32_bf16 v[132:135], v[120:123], v[24:27], v[132:135]
	v_mfma_f32_16x16x32_bf16 v[186:189], v[112:115], v[24:27], v[186:189]
	s_nop 6
	v_fma_f32 v132, v132, s33, -v181
	v_exp_f32_e32 v190, v132
	v_fma_f32 v132, v186, s33, -v181
	v_exp_f32_e32 v194, v132
	v_fma_f32 v132, v133, s33, -v181
	v_exp_f32_e32 v191, v132
	v_fma_f32 v132, v187, s33, -v181
	v_exp_f32_e32 v196, v132
	v_fma_f32 v132, v134, s33, -v181
	v_exp_f32_e32 v192, v132
	v_fma_f32 v132, v188, s33, -v181
	v_exp_f32_e32 v198, v132
	v_fma_f32 v132, v135, s33, -v181
	v_exp_f32_e32 v195, v132
	v_fma_f32 v132, v189, s33, -v181
	v_mfma_f32_16x16x32_bf16 v[186:189], v[116:119], v[36:39], 0
	v_exp_f32_e32 v200, v132
	v_mfma_f32_16x16x32_bf16 v[132:135], v[124:127], v[36:39], 0
	v_mfma_f32_16x16x32_bf16 v[186:189], v[112:115], v[44:47], v[186:189]
	v_mfma_f32_16x16x32_bf16 v[132:135], v[120:123], v[44:47], v[132:135]
	s_nop 6
	v_fma_f32 v186, v186, s33, -v182
	v_fma_f32 v132, v132, s33, -v182
	v_exp_f32_e32 v197, v186
	v_fma_f32 v186, v187, s33, -v182
	v_exp_f32_e32 v132, v132
	v_exp_f32_e32 v199, v186
	v_fma_f32 v186, v188, s33, -v182
	v_fma_f32 v133, v133, s33, -v182
	v_exp_f32_e32 v201, v186
	v_fma_f32 v186, v189, s33, -v182
	v_exp_f32_e32 v133, v133
	v_exp_f32_e32 v202, v186
	v_and_b32_e32 v186, 1, v159
	v_fma_f32 v134, v134, s33, -v182
	v_and_b32_e32 v188, 1, v128
	v_cmp_ne_u32_e32 vcc, 0, v186
	v_exp_f32_e32 v134, v134
	v_fma_f32 v135, v135, s33, -v182
	v_cndmask_b32_e32 v187, 0, v132, vcc
	v_cmp_ne_u32_e32 vcc, 0, v188
	v_and_b32_e32 v132, 2, v159
	v_and_b32_e32 v188, 2, v128
	v_cndmask_b32_e32 v186, 0, v190, vcc
	v_cmp_ne_u32_e32 vcc, 0, v132
	v_exp_f32_e32 v135, v135
	v_and_b32_e32 v132, 4, v159
	v_cndmask_b32_e32 v189, 0, v133, vcc
	v_cmp_ne_u32_e32 vcc, 0, v188
	v_and_b32_e32 v133, 4, v128
	s_nop 0
	v_cndmask_b32_e32 v188, 0, v191, vcc
	v_cmp_ne_u32_e32 vcc, 0, v132
	v_and_b32_e32 v132, 8, v159
	s_nop 0
	v_cndmask_b32_e32 v191, 0, v134, vcc
	v_cmp_ne_u32_e32 vcc, 0, v133
	v_and_b32_e32 v133, 8, v128
	s_nop 0
	v_cndmask_b32_e32 v190, 0, v192, vcc
	v_cmp_ne_u32_e32 vcc, 0, v132
	v_and_b32_e32 v132, 16, v159
	s_nop 0
	v_cndmask_b32_e32 v193, 0, v135, vcc
	v_cmp_ne_u32_e32 vcc, 0, v133
	v_and_b32_e32 v133, 16, v128
	s_nop 0
	v_cndmask_b32_e32 v192, 0, v195, vcc
	v_cmp_ne_u32_e32 vcc, 0, v132
	v_and_b32_e32 v132, 32, v159
	v_pk_add_f32 v[134:135], v[190:191], v[192:193]
	v_cndmask_b32_e32 v195, 0, v197, vcc
	v_cmp_ne_u32_e32 vcc, 0, v133
	v_and_b32_e32 v133, 32, v128
	s_nop 0
	v_cndmask_b32_e32 v194, 0, v194, vcc
	v_cmp_ne_u32_e32 vcc, 0, v132
	v_and_b32_e32 v132, 64, v159
	s_nop 0
	v_cndmask_b32_e32 v197, 0, v199, vcc
	v_cmp_ne_u32_e32 vcc, 0, v133
	v_and_b32_e32 v133, 64, v128
	v_and_b32_e32 v128, 0x80, v128
	v_cndmask_b32_e32 v196, 0, v196, vcc
	v_cmp_ne_u32_e32 vcc, 0, v132
	v_and_b32_e32 v132, 0x80, v159
	s_nop 0
	v_cndmask_b32_e32 v199, 0, v201, vcc
	v_cmp_ne_u32_e32 vcc, 0, v133
	s_nop 1
	v_cndmask_b32_e32 v198, 0, v198, vcc
	v_cmp_ne_u32_e32 vcc, 0, v132
	v_pk_add_f32 v[132:133], v[186:187], v[188:189]
	s_nop 0
	v_cndmask_b32_e32 v201, 0, v202, vcc
	v_cmp_ne_u32_e32 vcc, 0, v128
	v_pk_add_f32 v[132:133], v[132:133], v[134:135]
	v_pk_add_f32 v[134:135], v[194:195], v[196:197]
	v_cndmask_b32_e32 v200, 0, v200, vcc
	v_pk_add_f32 v[202:203], v[198:199], v[200:201]
	s_nop 0
	v_pk_add_f32 v[134:135], v[134:135], v[202:203]
	s_nop 0
	v_pk_add_f32 v[202:203], v[132:133], v[134:135]
	v_cvt_pk_bf16_f32 v132, v186, v188
	v_cvt_pk_bf16_f32 v133, v190, v192
	v_cvt_pk_bf16_f32 v134, v194, v196
	v_cvt_pk_bf16_f32 v135, v198, v200
	v_pk_add_f32 v[146:147], v[146:147], v[202:203]
	s_waitcnt vmcnt(3)
	v_mfma_f32_16x16x32_bf16 v[64:67], v[96:99], v[132:135], v[64:67]
	s_waitcnt vmcnt(2)
	v_mfma_f32_16x16x32_bf16 v[92:95], v[100:103], v[132:135], v[92:95]
	s_waitcnt vmcnt(1)
	v_mfma_f32_16x16x32_bf16 v[88:91], v[104:107], v[132:135], v[88:91]
	s_waitcnt vmcnt(0) lgkmcnt(0)
; #define MFMA16(a, b, c) __builtin_amdgcn_mfma_f32_16x16x32_bf16((a), (b), (c), 0, 0, 0)
; DI void attn_block(const Params& p, int isP, int sq, int c, int h) {
;     ...
;       for (int qt = 0; qt < 4; ++qt) {
;         if (qt < nqt) {
;           f32x4 sa = {0.f, 0.f, 0.f, 0.f}, sb = {0.f, 0.f, 0.f, 0.f};
;           sa = MFMA16(ka0, qf[qt][0], sa); sa = MFMA16(ka1, qf[qt][1], sa);
;           sb = MFMA16(kb0, qf[qt][0], sb); sb = MFMA16(kb1, qf[qt][1], sb);
;           const unsigned mb = (mw[qt] >> (fq * 8)) & 0xFFu;
;           float pr[8];
; #pragma unroll
;           for (int i = 0; i < 4; ++i) {
;             float pa_ = __builtin_amdgcn_exp2f(sa[i] * sc2 - mref[qt]);
;             float pb_ = __builtin_amdgcn_exp2f(sb[i] * sc2 - mref[qt]);
;             pr[i] = ((mb >> i) & 1u) ? pa_ : 0.f;
;             pr[4 + i] = ((mb >> (4 + i)) & 1u) ? pb_ : 0.f;
;           }
;           lsum[qt] += ((pr[0] + pr[1]) + (pr[2] + pr[3])) + ((pr[4] + pr[5]) + (pr[6] + pr[7]));
;           union { unsigned u[4]; bf16x8 v; } pk;
;           pk.u[0] = pack2(pr[0], pr[1]); pk.u[1] = pack2(pr[2], pr[3]); pk.u[2] = pack2(pr[4], pr[5]); pk.u[3] = pack2(pr[6], pr[7]);
; #pragma unroll
;           for (int dt = 0; dt < 4; ++dt) o[qt][dt] = MFMA16(vf[dt], pk.v, o[qt][dt]);
;         }
;       }
;       ka0 = nka0; ka1 = nka1; kb0 = nkb0; kb1 = nkb1;
; #pragma unroll
;       for (int dt = 0; dt < 4; ++dt) vf[dt] = nvf[dt];
; #pragma unroll
;       for (int qt = 0; qt < 4; ++qt) mw[qt] = nmw[qt];
;     }
	v_mfma_f32_16x16x32_bf16 v[84:87], v[108:111], v[132:135], v[84:87]
	v_cvt_pk_bf16_f32 v132, v187, v189
	v_cvt_pk_bf16_f32 v133, v191, v193
	v_cvt_pk_bf16_f32 v134, v195, v197
	v_cvt_pk_bf16_f32 v135, v199, v201
	v_mfma_f32_16x16x32_bf16 v[186:189], v[116:119], v[48:51], 0
	s_nop 0
	v_mfma_f32_16x16x32_bf16 v[80:83], v[96:99], v[132:135], v[80:83]
	v_mfma_f32_16x16x32_bf16 v[76:79], v[100:103], v[132:135], v[76:79]
	v_mfma_f32_16x16x32_bf16 v[72:75], v[104:107], v[132:135], v[72:75]
	v_mfma_f32_16x16x32_bf16 v[68:71], v[108:111], v[132:135], v[68:71]
	v_mfma_f32_16x16x32_bf16 v[132:135], v[124:127], v[48:51], 0
	v_mfma_f32_16x16x32_bf16 v[124:127], v[124:127], v[56:59], 0
	v_mfma_f32_16x16x32_bf16 v[132:135], v[120:123], v[52:55], v[132:135]
	v_mfma_f32_16x16x32_bf16 v[120:123], v[120:123], v[60:63], v[124:127]
	v_mfma_f32_16x16x32_bf16 v[116:119], v[116:119], v[56:59], 0
	s_nop 5
	v_fma_f32 v128, v132, s33, -v183
	v_exp_f32_e32 v128, v128
	v_fma_f32 v133, v133, s33, -v183
	v_mfma_f32_16x16x32_bf16 v[186:189], v[112:115], v[52:55], v[186:189]
	v_exp_f32_e32 v133, v133
	v_fma_f32 v134, v134, s33, -v183
	v_exp_f32_e32 v134, v134
	v_mfma_f32_16x16x32_bf16 v[112:115], v[112:115], v[60:63], v[116:119]
	v_fma_f32 v135, v135, s33, -v183
	s_nop 2
	v_fma_f32 v132, v186, s33, -v183
	v_fma_f32 v186, v188, s33, -v183
	v_fma_f32 v116, v120, s33, -v184
	v_fma_f32 v117, v121, s33, -v184
	v_exp_f32_e32 v116, v116
	v_exp_f32_e32 v118, v117
	v_fma_f32 v117, v122, s33, -v184
	v_exp_f32_e32 v120, v117
	v_fma_f32 v117, v123, s33, -v184
	v_lshrrev_b32_e32 v188, v137, v204
	v_exp_f32_e32 v122, v117
	v_and_b32_e32 v117, 1, v188
	v_and_b32_e32 v119, 1, v185
	v_cmp_ne_u32_e32 vcc, 0, v117
	v_and_b32_e32 v121, 2, v185
	v_exp_f32_e32 v135, v135
	v_cndmask_b32_e32 v117, 0, v116, vcc
	v_cmp_ne_u32_e32 vcc, 0, v119
	v_and_b32_e32 v119, 2, v188
	v_fma_f32 v112, v112, s33, -v184
	v_cndmask_b32_e32 v116, 0, v128, vcc
	v_cmp_ne_u32_e32 vcc, 0, v119
	v_and_b32_e32 v123, 4, v185
	v_exp_f32_e32 v112, v112
	v_cndmask_b32_e32 v119, 0, v118, vcc
	v_cmp_ne_u32_e32 vcc, 0, v121
	v_and_b32_e32 v121, 4, v188
	v_exp_f32_e32 v132, v132
	v_cndmask_b32_e32 v118, 0, v133, vcc
	v_cmp_ne_u32_e32 vcc, 0, v121
	v_fma_f32 v113, v113, s33, -v184
	v_and_b32_e32 v124, 8, v185
	v_cndmask_b32_e32 v121, 0, v120, vcc
	v_cmp_ne_u32_e32 vcc, 0, v123
	v_and_b32_e32 v123, 8, v188
	v_fma_f32 v159, v187, s33, -v183
	v_cndmask_b32_e32 v120, 0, v134, vcc
	v_cmp_ne_u32_e32 vcc, 0, v123
	v_exp_f32_e32 v113, v113
	v_exp_f32_e32 v159, v159
	v_cndmask_b32_e32 v123, 0, v122, vcc
	v_cmp_ne_u32_e32 vcc, 0, v124
	v_and_b32_e32 v124, 16, v188
	v_fma_f32 v114, v114, s33, -v184
	v_cndmask_b32_e32 v122, 0, v135, vcc
	v_and_b32_e32 v126, 16, v185
	v_cmp_ne_u32_e32 vcc, 0, v124
	v_exp_f32_e32 v114, v114
	v_exp_f32_e32 v186, v186
	v_cndmask_b32_e32 v125, 0, v112, vcc
	v_cmp_ne_u32_e32 vcc, 0, v126
	v_and_b32_e32 v112, 32, v188
	v_fma_f32 v115, v115, s33, -v184
	v_cndmask_b32_e32 v124, 0, v132, vcc
	v_and_b32_e32 v126, 32, v185
	v_cmp_ne_u32_e32 vcc, 0, v112
	v_fma_f32 v187, v189, s33, -v183
	v_exp_f32_e32 v115, v115
	v_cndmask_b32_e32 v127, 0, v113, vcc
	v_cmp_ne_u32_e32 vcc, 0, v126
	v_and_b32_e32 v112, 64, v188
	v_exp_f32_e32 v187, v187
	v_cndmask_b32_e32 v126, 0, v159, vcc
	v_and_b32_e32 v113, 64, v185
	v_cmp_ne_u32_e32 vcc, 0, v112
	v_and_b32_e32 v112, 0x80, v188
	s_nop 0
	v_cndmask_b32_e32 v133, 0, v114, vcc
	v_cmp_ne_u32_e32 vcc, 0, v113
	v_and_b32_e32 v113, 0x80, v185
	s_nop 0
	v_cndmask_b32_e32 v132, 0, v186, vcc
	v_cmp_ne_u32_e32 vcc, 0, v112
	s_nop 1
	v_cndmask_b32_e32 v135, 0, v115, vcc
	v_cmp_ne_u32_e32 vcc, 0, v113
	v_pk_add_f32 v[112:113], v[116:117], v[118:119]
	v_pk_add_f32 v[114:115], v[120:121], v[122:123]
	v_cndmask_b32_e32 v134, 0, v187, vcc
	v_pk_add_f32 v[112:113], v[112:113], v[114:115]
	v_pk_add_f32 v[114:115], v[124:125], v[126:127]
	v_pk_add_f32 v[186:187], v[132:133], v[134:135]
	s_nop 0
	v_pk_add_f32 v[114:115], v[114:115], v[186:187]
	s_nop 0
	v_pk_add_f32 v[186:187], v[112:113], v[114:115]
	v_cvt_pk_bf16_f32 v112, v116, v118
	v_cvt_pk_bf16_f32 v113, v120, v122
	v_cvt_pk_bf16_f32 v114, v124, v126
	v_cvt_pk_bf16_f32 v115, v132, v134
	v_pk_add_f32 v[142:143], v[142:143], v[186:187]
	s_nop 0
	v_mfma_f32_16x16x32_bf16 v[40:43], v[96:99], v[112:115], v[40:43]
	v_mfma_f32_16x16x32_bf16 v[32:35], v[100:103], v[112:115], v[32:35]
	v_mfma_f32_16x16x32_bf16 v[28:31], v[104:107], v[112:115], v[28:31]
	v_mfma_f32_16x16x32_bf16 v[20:23], v[108:111], v[112:115], v[20:23]
	v_cvt_pk_bf16_f32 v112, v117, v119
	v_cvt_pk_bf16_f32 v113, v121, v123
	v_cvt_pk_bf16_f32 v114, v125, v127
	v_cvt_pk_bf16_f32 v115, v133, v135
	s_nop 1
	v_mfma_f32_16x16x32_bf16 v[12:15], v[96:99], v[112:115], v[12:15]
	v_mfma_f32_16x16x32_bf16 v[8:11], v[100:103], v[112:115], v[8:11]
	v_mfma_f32_16x16x32_bf16 v[4:7], v[104:107], v[112:115], v[4:7]
	v_mfma_f32_16x16x32_bf16 v[0:3], v[108:111], v[112:115], v[0:3]
	s_cbranch_scc1 .LBB0_4861
